# v078: v077 + MLA loop: row-sum accumulate chain issued inside the P.V MFMA burst, next-iteration pointer updates before the pair barrier
# speedup vs baseline: 1.0024x; 1.0020x over previous
; __device__ __forceinline__ unsigned cvtpk_s(float lo, float hi) { f32x2_t v = {lo, hi}; bf16x2_t b = __builtin_convertvector(v, bf16x2_t); return __builtin_bit_cast(unsigned, b); }
; #define ATT_STOREV(sl) do { _Pragma("unroll") for (int i = 0; i < VPT; ++i) *(LAS u32x4*)(lds + C::VOFF + (sl) * C::VBYTES + i * (512 / VCH) * VP + ldsV) = vst[i]; } while (0)
; template <int DQK, int DKA, int DV> ...
;     ...
;     for (int t = 0; t < NT; ++t) {
;         const int ks1 = (t + 1) & 3;
;         if (t + 3 < NT) ATT_STOREK((t + 3) & 3);
;         if (t + 2 < NT) ATT_STOREV((t + 2) & 3);
;         if (t + 4 < NT) ATT_LOADK(t + 4);
;         if (t + 3 < NT) ATT_LOADV(t + 3);
;     ...
;             { float rs = 0.f;
; #pragma unroll
;               for (int i = 0; i < 16; ++i) { p0[i] = __builtin_amdgcn_exp2f(NEGM ? p0[i] : p0[i] - m); p1[i] = __builtin_amdgcn_exp2f(NEGM ? p1[i] : p1[i] - m); rs += p0[i] + p1[i]; }
;               l += rs;
; #pragma unroll
;               for (int s = 0; s < 2; ++s) { u32x4 w0, w1;
;                 w0.x = cvtpk_s(p0[8 * s], p0[8 * s + 1]); w0.y = cvtpk_s(p0[8 * s + 2], p0[8 * s + 3]); w0.z = cvtpk_s(p0[8 * s + 4], p0[8 * s + 5]); w0.w = cvtpk_s(p0[8 * s + 6], p0[8 * s + 7]);
;                 w1.x = cvtpk_s(p1[8 * s], p1[8 * s + 1]); w1.y = cvtpk_s(p1[8 * s + 2], p1[8 * s + 3]); w1.z = cvtpk_s(p1[8 * s + 4], p1[8 * s + 5]); w1.w = cvtpk_s(p1[8 * s + 6], p1[8 * s + 7]);
;                 pf[s] = __builtin_bit_cast(bf16x8, w0); pf[2 + s] = __builtin_bit_cast(bf16x8, w1); } }
;             __builtin_amdgcn_sched_barrier(0);
;             if (NV == 2) {
;                 __builtin_amdgcn_s_setprio(3); ATT_PV(0); __builtin_amdgcn_s_setprio(0);
;                 __builtin_amdgcn_sched_barrier(0);
;                 if (t + 1 < NT) ATT_KFRAG(ks1);
;             } else {
;                 __builtin_amdgcn_s_setprio(3); ATT_PV(0); __builtin_amdgcn_s_setprio(0);
;                 __builtin_amdgcn_sched_barrier(0);
;                 ATT_VFRAG(2);
;                 __builtin_amdgcn_sched_barrier(0);
;                 __builtin_amdgcn_s_setprio(3); ATT_PV(2); __builtin_amdgcn_s_setprio(0);
;                 __builtin_amdgcn_sched_barrier(0);
;                 if (t + 1 < NT) ATT_KFRAG(ks1);
;             }
;             __builtin_amdgcn_sched_barrier(0);
;         }
;         if (t & 1) asm volatile("s_waitcnt lgkmcnt(0)\n\ts_barrier" ::: "memory");
.LBB0_612:
	v_exp_f32_e32 v160, v64
	v_exp_f32_e32 v161, v48
	v_exp_f32_e32 v48, v65
	v_exp_f32_e32 v162, v49
	v_exp_f32_e32 v49, v66
	v_exp_f32_e32 v166, v67
	v_exp_f32_e32 v65, v52
	v_exp_f32_e32 v64, v53
	v_exp_f32_e32 v67, v54
	v_exp_f32_e32 v66, v55
	v_exp_f32_e32 v149, v72
	v_exp_f32_e32 v148, v73
	v_exp_f32_e32 v73, v74
	v_exp_f32_e32 v153, v58
	v_exp_f32_e32 v72, v75
	v_exp_f32_e32 v152, v59
	v_exp_f32_e32 v59, v76
	v_exp_f32_e32 v75, v60
	v_exp_f32_e32 v58, v77
	v_exp_f32_e32 v74, v61
	v_exp_f32_e32 v61, v78
	v_exp_f32_e32 v77, v62
	v_exp_f32_e32 v60, v79
	v_exp_f32_e32 v76, v63
	v_exp_f32_e32 v151, v56
	v_exp_f32_e32 v150, v57
	v_exp_f32_e32 v165, v50
	v_exp_f32_e32 v167, v51
	v_exp_f32_e32 v51, v68
	v_exp_f32_e32 v50, v69
	v_pk_add_f32 v[156:157], v[58:59], v[74:75]
	v_pk_add_f32 v[158:159], v[60:61], v[76:77]
	v_cvt_pk_bf16_f32 v54, v65, v64
	v_cvt_pk_bf16_f32 v55, v67, v66
	v_cvt_pk_bf16_f32 v56, v149, v148
	v_cvt_pk_bf16_f32 v57, v73, v72
	v_cvt_pk_bf16_f32 v58, v59, v58
	v_cvt_pk_bf16_f32 v59, v61, v60
	v_add_f32_e32 v163, v160, v161
	v_pk_add_f32 v[68:69], v[50:51], v[64:65]
	v_cvt_pk_bf16_f32 v60, v151, v150
	v_cvt_pk_bf16_f32 v61, v153, v152
	v_pk_mov_b32 v[64:65], v[76:77], v[76:77] op_sel:[1,0]
	v_add_f32_e32 v164, v48, v162
	v_cvt_pk_bf16_f32 v62, v75, v74
	v_cvt_pk_bf16_f32 v63, v64, v65
	v_exp_f32_e32 v53, v70
	v_exp_f32_e32 v52, v71
	v_add_f32_e32 v168, v49, v165
	v_add_f32_e32 v169, v166, v167
	v_pk_add_f32 v[70:71], v[52:53], v[66:67]
	v_pk_add_f32 v[78:79], v[148:149], v[150:151]
	v_pk_add_f32 v[154:155], v[72:73], v[152:153]
	v_cvt_pk_bf16_f32 v48, v160, v48
	v_cvt_pk_bf16_f32 v49, v49, v166
	v_cvt_pk_bf16_f32 v50, v51, v50
	v_cvt_pk_bf16_f32 v51, v53, v52
	v_cvt_pk_bf16_f32 v52, v161, v162
	v_cvt_pk_bf16_f32 v53, v165, v167
	s_setprio 3
	s_waitcnt lgkmcnt(14)
	v_mfma_f32_32x32x16_bf16 v[0:15], v[144:147], v[48:51], v[0:15]
	v_add_f32_e32 v64, 0, v163
	v_add_f32_e32 v64, v164, v64
	s_waitcnt lgkmcnt(12)
	v_mfma_f32_32x32x16_bf16 v[16:31], v[140:143], v[48:51], v[16:31]
	v_add_f32_e32 v64, v168, v64
	v_add_f32_e32 v64, v169, v64
	s_waitcnt lgkmcnt(10)
	v_mfma_f32_32x32x16_bf16 v[0:15], v[136:139], v[56:59], v[0:15]
	v_add_f32_e32 v64, v69, v64
	v_add_f32_e32 v64, v68, v64
	s_waitcnt lgkmcnt(8)
	v_mfma_f32_32x32x16_bf16 v[16:31], v[132:135], v[56:59], v[16:31]
	v_add_f32_e32 v64, v71, v64
	v_add_f32_e32 v64, v70, v64
	s_waitcnt lgkmcnt(6)
	v_mfma_f32_32x32x16_bf16 v[0:15], v[128:131], v[52:55], v[0:15]
	v_add_f32_e32 v64, v79, v64
	v_add_f32_e32 v64, v78, v64
	s_waitcnt lgkmcnt(4)
	v_mfma_f32_32x32x16_bf16 v[16:31], v[124:127], v[52:55], v[16:31]
	v_add_f32_e32 v64, v155, v64
	v_add_f32_e32 v64, v154, v64
	s_waitcnt lgkmcnt(2)
	v_mfma_f32_32x32x16_bf16 v[0:15], v[120:123], v[60:63], v[0:15]
	v_add_f32_e32 v64, v157, v64
	v_add_f32_e32 v64, v156, v64
	s_waitcnt lgkmcnt(0)
	v_mfma_f32_32x32x16_bf16 v[16:31], v[116:119], v[60:63], v[16:31]
	v_add_f32_e32 v64, v159, v64
	v_add_f32_e32 v64, v158, v64
	v_add_f32_e32 v185, v185, v64
	s_setprio 0
	s_mul_i32 s22, s62, 0x3400
	v_add_u32_e32 v48, s22, v197
	ds_read_b128 v[132:135], v48 offset:6816
	ds_read_b128 v[140:143], v48 offset:6784
	ds_read_b128 v[136:139], v48 offset:160
	ds_read_b128 v[144:147], v48 offset:128
	ds_read_b128 v[148:151], v48 offset:6752
	ds_read_b128 v[156:159], v48 offset:6720
	ds_read_b128 v[152:155], v48 offset:96
	ds_read_b128 v[160:163], v48 offset:64
	ds_read_b128 v[172:175], v48
	ds_read_b128 v[168:171], v48 offset:32
	ds_read_b128 v[164:167], v48 offset:6688
	ds_read_b128 v[176:179], v48 offset:6656
.LBB0_613:
	s_bitcmp0_b32 s60, 0
	s_cbranch_scc1 .LBB0_601
	s_add_i32 s1, s1, 1
	s_add_i32 s60, s8, s1
	s_add_i32 s9, s9, 64
	s_mov_b64 s[22:23], 0x1000
	v_lshl_add_u64 v[186:187], v[186:187], 0, s[22:23]
	v_lshl_add_u64 v[188:189], v[188:189], 0, s[6:7]
	s_cmp_lg_u32 s60, 3
	v_lshl_add_u64 v[190:191], v[190:191], 0, s[6:7]
	s_waitcnt lgkmcnt(0)
	s_barrier
	s_cbranch_scc0 .LBB0_622
	s_branch .LBB0_602
